# combo + closed-form unit assignment (k=2) replacing the 32-iteration prefix-sum loop
# speedup vs baseline: 1.0077x; 1.0038x over previous
; DI float lo16(unsigned w) { return __uint_as_float(w << 16); }
; DI float hi16(unsigned w) { return __uint_as_float(w & 0xffff0000u); }
; DI float siluf_(float x) { return x / (1.f + __expf(-x)); }
; DI void nsa_item(const Params& p, int it, char* lds) {
;     ...
; #pragma unroll
;   for (int r = 0; r < 16; ++r) { ya[0][r] = yst[r * 256 + tid]; ya[1][r] = yst[(16 + r) * 256 + tid]; }
;   lsum += __shfl_xor(lsum, 32, 64);
;   const float il = g1 / lsum;
;   const u16* ow = (const u16*)(ws_ + OFF_OWIN);
;   u16* y = (u16*)(ws_ + OFF_XB);
; #pragma unroll
;   for (int db = 0; db < 2; ++db)
; #pragma unroll
;     for (int g = 0; g < 4; ++g) {
;       const int col = h * 64 + 32 * db + 8 * g + 4 * hi;
;       const u32x2 w = *(const u32x2*)(ow + tok * 256 + col), az = *(const u32x2*)(proj + tok * NP + C_AZ + col);
;       const float v0 = (ya[db][4 * g] + o[db][4 * g] * il + g2 * lo16(w[0])) * siluf_(lo16(az[0]));
;       const float v1 = (ya[db][4 * g + 1] + o[db][4 * g + 1] * il + g2 * hi16(w[0])) * siluf_(hi16(az[0]));
;       const float v2 = (ya[db][4 * g + 2] + o[db][4 * g + 2] * il + g2 * lo16(w[1])) * siluf_(lo16(az[1]));
;       const float v3 = (ya[db][4 * g + 3] + o[db][4 * g + 3] * il + g2 * hi16(w[1])) * siluf_(hi16(az[1]));
;       u32x2 v; v[0] = pk2(v0, v1); v[1] = pk2(v2, v3);
;       *(u32x2*)(y + tok * 1024 + col) = v;
;     }
.LBB0_405:
	v_lshlrev_b32_e32 v32, 16, v155
	v_mul_f32_e32 v32, 0xbfb8aa3b, v32
	v_exp_f32_e32 v32, v32
	ds_bpermute_b32 v181, v158, v151
	v_mov_b32_e32 v147, v179
	v_lshlrev_b64 v[72:73], 11, v[146:147]
	v_add_f32_e32 v32, 1.0, v32
	v_readlane_b32 s13, v234, 36
	v_readlane_b32 s12, v234, 33
	v_readlane_b32 s14, v234, 37
	v_rcp_f32_e32 v32, v32
	s_nop 0
	v_lshlrev_b32_e32 v33, 16, v154
	v_mul_f32_e32 v33, 0xbfb8aa3b, v33
	v_exp_f32_e32 v150, v33
	ds_read2st64_b32 v[70:71], v161 offset0:144 offset1:148
	ds_read2st64_b32 v[54:55], v161 offset0:208 offset1:212
	ds_read2st64_b32 v[68:69], v161 offset0:152 offset1:156
	ds_read2st64_b32 v[52:53], v161 offset0:216 offset1:220
	ds_read2st64_b32 v[66:67], v161 offset0:160 offset1:164
	ds_read2st64_b32 v[50:51], v161 offset0:224 offset1:228
	ds_read2st64_b32 v[64:65], v161 offset0:168 offset1:172
	ds_read2st64_b32 v[48:49], v161 offset0:232 offset1:236
	ds_read2st64_b32 v[62:63], v161 offset0:176 offset1:180
	ds_read2st64_b32 v[46:47], v161 offset0:240 offset1:244
	ds_read2st64_b32 v[60:61], v161 offset0:184 offset1:188
	ds_read2st64_b32 v[44:45], v161 offset0:248 offset1:252
	ds_read2st64_b32 v[58:59], v161 offset0:192 offset1:196
	ds_read_b32 v38, v162
	ds_read_b32 v39, v163
	ds_read2st64_b32 v[56:57], v161 offset0:200 offset1:204
	ds_read_b32 v34, v164
	ds_read_b32 v35, v165
	s_waitcnt lgkmcnt(14)
	v_pk_add_f32 v[36:37], v[150:151], v[180:181]
	s_nop 0
	s_nop 0
	v_rcp_f32_e32 v33, v36
	s_nop 0
	v_readlane_b32 s0, v234, 38
	v_readlane_b32 s1, v234, 39
	v_or_b32_e32 v40, v156, v148
	v_lshlrev_b64 v[42:43], 9, v[146:147]
	v_ashrrev_i32_e32 v41, 31, v40
	v_lshl_add_u64 v[42:43], s[0:1], 0, v[42:43]
	v_lshlrev_b64 v[74:75], 1, v[40:41]
	v_lshl_add_u64 v[72:73], s[0:1], 0, v[72:73]
	v_lshl_add_u64 v[40:41], v[42:43], 0, v[74:75]
	s_mov_b64 s[0:1], 0xb390000
	v_lshl_add_u64 v[42:43], v[40:41], 0, s[0:1]
	s_mov_b32 s0, 0xb390000
	v_add_co_u32_e32 v40, vcc, s0, v40
	v_rcp_f32_e32 v36, v37
	s_nop 0
	v_mul_f32_e32 v36, v33, v36
	s_nop 0
	v_addc_co_u32_e32 v41, vcc, 0, v41, vcc
	global_load_dwordx2 v[76:77], v[40:41], off
	v_lshl_add_u64 v[40:41], v[144:145], 0, v[74:75]
	global_load_dwordx2 v[78:79], v[40:41], off offset:1280
	s_waitcnt vmcnt(0)
	v_and_b32_e32 v37, 0xffff0000, v78
	v_lshlrev_b32_e32 v33, 16, v78
	v_pk_fma_f32 v[16:17], v[16:17], v[36:37], v[70:71] op_sel_hi:[1,0,1]
	v_lshlrev_b32_e32 v70, 16, v76
	v_and_b32_e32 v71, 0xffff0000, v76
	v_mul_f32_e32 v78, 0xbfb8aa3b, v33
	v_pk_fma_f32 v[16:17], v[32:33], v[70:71], v[16:17] op_sel_hi:[0,1,1]
	v_mul_f32_e32 v70, 0xbfb8aa3b, v37
	v_exp_f32_e32 v80, v78
	v_exp_f32_e32 v81, v70
	s_nop 0
	v_pk_add_f32 v[70:71], v[80:81], 1.0 op_sel_hi:[1,0]
	s_nop 0
	s_nop 0
	v_rcp_f32_e32 v71, v71
	s_nop 0
	v_mul_f32_e32 v71, v37, v71
	s_nop 0
	v_rcp_f32_e32 v70, v70
	s_nop 0
	v_mul_f32_e32 v70, v33, v70
	v_and_b32_e32 v37, 0xffff0000, v79
	v_lshlrev_b32_e32 v33, 16, v79
	v_pk_fma_f32 v[18:19], v[18:19], v[36:37], v[68:69] op_sel_hi:[1,0,1]
	v_lshlrev_b32_e32 v68, 16, v77
	v_and_b32_e32 v69, 0xffff0000, v77
	v_pk_mul_f32 v[16:17], v[16:17], v[70:71]
	v_mul_f32_e32 v70, 0xbfb8aa3b, v33
	v_pk_fma_f32 v[18:19], v[32:33], v[68:69], v[18:19] op_sel_hi:[0,1,1]
	v_mul_f32_e32 v68, 0xbfb8aa3b, v37
	v_exp_f32_e32 v70, v70
	v_exp_f32_e32 v71, v68
	s_nop 0
	v_pk_add_f32 v[68:69], v[70:71], 1.0 op_sel_hi:[1,0]
	s_nop 0
	s_nop 0
	v_rcp_f32_e32 v69, v69
	s_nop 0
	v_mul_f32_e32 v69, v37, v69
	s_mov_b64 s[0:1], 0x2a40000
	v_rcp_f32_e32 v68, v68
	s_nop 0
	v_mul_f32_e32 v68, v33, v68
	v_pk_mul_f32 v[18:19], v[18:19], v[68:69]
	v_cvt_pk_bf16_f32 v68, v16, v17
	v_cvt_pk_bf16_f32 v69, v18, v19
	v_lshl_add_u64 v[18:19], v[72:73], 0, v[74:75]
	v_lshl_add_u64 v[16:17], v[18:19], 0, s[0:1]
	v_add_co_u32_e32 v18, vcc, s74, v18
	s_nop 1
	v_addc_co_u32_e32 v19, vcc, 0, v19, vcc
	global_store_dwordx2 v[18:19], v[68:69], off
	global_load_dwordx2 v[18:19], v[42:43], off offset:16
	s_nop 0
	global_load_dwordx2 v[68:69], v[40:41], off offset:1296
	s_waitcnt vmcnt(0)
	v_lshlrev_b32_e32 v33, 16, v68
	v_and_b32_e32 v37, 0xffff0000, v68
	v_mul_f32_e32 v68, 0xbfb8aa3b, v33
	s_waitcnt lgkmcnt(13)
	v_pk_fma_f32 v[20:21], v[20:21], v[36:37], v[66:67] op_sel_hi:[1,0,1]
	v_lshlrev_b32_e32 v66, 16, v18
	v_and_b32_e32 v67, 0xffff0000, v18
	v_mul_f32_e32 v18, 0xbfb8aa3b, v37
	v_exp_f32_e32 v70, v68
	v_exp_f32_e32 v71, v18
	v_pk_fma_f32 v[20:21], v[32:33], v[66:67], v[20:21] op_sel_hi:[0,1,1]
	v_pk_add_f32 v[66:67], v[70:71], 1.0 op_sel_hi:[1,0]
	s_nop 0
	s_nop 0
	v_rcp_f32_e32 v67, v67
	s_nop 0
	v_mul_f32_e32 v67, v37, v67
	s_nop 0
	v_rcp_f32_e32 v66, v66
	s_nop 0
	v_mul_f32_e32 v66, v33, v66
	v_lshlrev_b32_e32 v33, 16, v69
	v_and_b32_e32 v37, 0xffff0000, v69
	v_mul_f32_e32 v18, 0xbfb8aa3b, v33
	s_waitcnt lgkmcnt(11)
	v_pk_fma_f32 v[22:23], v[22:23], v[36:37], v[64:65] op_sel_hi:[1,0,1]
	v_lshlrev_b32_e32 v64, 16, v19
	v_and_b32_e32 v65, 0xffff0000, v19
	v_mul_f32_e32 v19, 0xbfb8aa3b, v37
	v_exp_f32_e32 v18, v18
	v_exp_f32_e32 v19, v19
	v_pk_fma_f32 v[22:23], v[32:33], v[64:65], v[22:23] op_sel_hi:[0,1,1]
	v_pk_mul_f32 v[20:21], v[20:21], v[66:67]
	v_pk_add_f32 v[18:19], v[18:19], 1.0 op_sel_hi:[1,0]
	s_nop 0
	v_cvt_pk_bf16_f32 v20, v20, v21
	v_rcp_f32_e32 v19, v19
	s_nop 0
	v_mul_f32_e32 v19, v37, v19
	v_div_scale_f32 v37, s[0:1], v18, v18, v33
	v_rcp_f32_e32 v64, v37
	s_nop 0
	v_fma_f32 v65, -v37, v64, 1.0
	v_fmac_f32_e32 v64, v65, v64
	v_div_scale_f32 v65, vcc, v33, v18, v33
	v_mul_f32_e32 v66, v65, v64
	v_fma_f32 v67, -v37, v66, v65
	v_fmac_f32_e32 v66, v67, v64
	v_fma_f32 v37, -v37, v66, v65
	v_div_fmas_f32 v37, v37, v64, v66
	v_div_fixup_f32 v18, v37, v18, v33
	v_pk_mul_f32 v[18:19], v[22:23], v[18:19]
	s_waitcnt lgkmcnt(9)
; DI float lo16(unsigned w) { return __uint_as_float(w << 16); }
; DI float hi16(unsigned w) { return __uint_as_float(w & 0xffff0000u); }
; DI float siluf_(float x) { return x / (1.f + __expf(-x)); }
; DI void nsa_item(const Params& p, int it, char* lds) {
;     ...
; #pragma unroll
;   for (int db = 0; db < 2; ++db)
; #pragma unroll
;     for (int g = 0; g < 4; ++g) {
;       const int col = h * 64 + 32 * db + 8 * g + 4 * hi;
;       const u32x2 w = *(const u32x2*)(ow + tok * 256 + col), az = *(const u32x2*)(proj + tok * NP + C_AZ + col);
;       const float v0 = (ya[db][4 * g] + o[db][4 * g] * il + g2 * lo16(w[0])) * siluf_(lo16(az[0]));
;       const float v1 = (ya[db][4 * g + 1] + o[db][4 * g + 1] * il + g2 * hi16(w[0])) * siluf_(hi16(az[0]));
;       const float v2 = (ya[db][4 * g + 2] + o[db][4 * g + 2] * il + g2 * lo16(w[1])) * siluf_(lo16(az[1]));
;       const float v3 = (ya[db][4 * g + 3] + o[db][4 * g + 3] * il + g2 * hi16(w[1])) * siluf_(hi16(az[1]));
;       u32x2 v; v[0] = pk2(v0, v1); v[1] = pk2(v2, v3);
;       *(u32x2*)(y + tok * 1024 + col) = v;
;     }
	v_pk_fma_f32 v[24:25], v[24:25], v[36:37], v[62:63] op_sel_hi:[1,0,1]
	v_cvt_pk_bf16_f32 v21, v18, v19
	global_store_dwordx2 v[16:17], v[20:21], off offset:16
	global_load_dwordx2 v[18:19], v[42:43], off offset:32
	s_nop 0
	global_load_dwordx2 v[20:21], v[40:41], off offset:1312
	s_waitcnt vmcnt(1)
	v_lshlrev_b32_e32 v62, 16, v18
	s_waitcnt vmcnt(0)
	v_lshlrev_b32_e32 v33, 16, v20
	v_and_b32_e32 v20, 0xffff0000, v20
	v_mul_f32_e32 v22, 0xbfb8aa3b, v33
	v_and_b32_e32 v63, 0xffff0000, v18
	v_mul_f32_e32 v18, 0xbfb8aa3b, v20
	v_exp_f32_e32 v22, v22
	v_exp_f32_e32 v23, v18
	v_pk_fma_f32 v[24:25], v[32:33], v[62:63], v[24:25] op_sel_hi:[0,1,1]
	v_pk_add_f32 v[22:23], v[22:23], 1.0 op_sel_hi:[1,0]
	s_nop 0
	s_nop 0
	v_rcp_f32_e32 v23, v23
	s_nop 0
	v_mul_f32_e32 v23, v20, v23
	s_nop 0
	v_rcp_f32_e32 v22, v22
	s_nop 0
	v_mul_f32_e32 v22, v33, v22
	v_lshlrev_b32_e32 v33, 16, v21
	v_and_b32_e32 v37, 0xffff0000, v21
	v_pk_mul_f32 v[22:23], v[24:25], v[22:23]
	v_mul_f32_e32 v18, 0xbfb8aa3b, v33
	v_lshlrev_b32_e32 v24, 16, v19
	v_and_b32_e32 v25, 0xffff0000, v19
	v_mul_f32_e32 v19, 0xbfb8aa3b, v37
	v_exp_f32_e32 v18, v18
	v_exp_f32_e32 v19, v19
	s_waitcnt lgkmcnt(7)
	v_pk_fma_f32 v[20:21], v[26:27], v[36:37], v[60:61] op_sel_hi:[1,0,1]
	v_pk_add_f32 v[18:19], v[18:19], 1.0 op_sel_hi:[1,0]
	v_pk_fma_f32 v[20:21], v[32:33], v[24:25], v[20:21] op_sel_hi:[0,1,1]
	s_nop 0
	v_rcp_f32_e32 v19, v19
	s_nop 0
	v_mul_f32_e32 v19, v37, v19
	v_div_scale_f32 v24, s[0:1], v18, v18, v33
	v_rcp_f32_e32 v25, v24
	s_nop 0
	v_fma_f32 v26, -v24, v25, 1.0
	v_fmac_f32_e32 v25, v26, v25
	v_div_scale_f32 v26, vcc, v33, v18, v33
	v_mul_f32_e32 v27, v26, v25
	v_fma_f32 v37, -v24, v27, v26
	v_fmac_f32_e32 v27, v37, v25
	v_fma_f32 v24, -v24, v27, v26
	v_div_fmas_f32 v24, v24, v25, v27
	v_div_fixup_f32 v18, v24, v18, v33
	v_pk_mul_f32 v[18:19], v[20:21], v[18:19]
	v_cvt_pk_bf16_f32 v20, v22, v23
	v_cvt_pk_bf16_f32 v21, v18, v19
	global_store_dwordx2 v[16:17], v[20:21], off offset:32
	global_load_dwordx2 v[18:19], v[42:43], off offset:48
	s_nop 0
	global_load_dwordx2 v[20:21], v[40:41], off offset:1328
	s_waitcnt lgkmcnt(5)
	v_pk_fma_f32 v[24:25], v[28:29], v[36:37], v[58:59] op_sel_hi:[1,0,1]
	v_pk_fma_f32 v[0:1], v[0:1], v[36:37], v[54:55] op_sel_hi:[1,0,1]
	v_pk_fma_f32 v[2:3], v[2:3], v[36:37], v[52:53] op_sel_hi:[1,0,1]
	v_pk_fma_f32 v[4:5], v[4:5], v[36:37], v[50:51] op_sel_hi:[1,0,1]
	s_waitcnt vmcnt(1)
	v_lshlrev_b32_e32 v26, 16, v18
	s_waitcnt vmcnt(0)
	v_lshlrev_b32_e32 v33, 16, v20
	v_and_b32_e32 v20, 0xffff0000, v20
	v_mul_f32_e32 v22, 0xbfb8aa3b, v33
	v_and_b32_e32 v27, 0xffff0000, v18
	v_mul_f32_e32 v18, 0xbfb8aa3b, v20
	v_exp_f32_e32 v22, v22
	v_exp_f32_e32 v23, v18
	v_pk_fma_f32 v[24:25], v[32:33], v[26:27], v[24:25] op_sel_hi:[0,1,1]
	v_pk_add_f32 v[22:23], v[22:23], 1.0 op_sel_hi:[1,0]
	s_nop 0
	s_nop 0
	v_rcp_f32_e32 v23, v23
	s_nop 0
	v_mul_f32_e32 v23, v20, v23
	s_nop 0
	v_rcp_f32_e32 v22, v22
	s_nop 0
	v_mul_f32_e32 v22, v33, v22
	v_lshlrev_b32_e32 v26, 16, v21
	v_and_b32_e32 v27, 0xffff0000, v21
	v_pk_mul_f32 v[22:23], v[24:25], v[22:23]
	v_mul_f32_e32 v18, 0xbfb8aa3b, v26
	v_lshlrev_b32_e32 v24, 16, v19
	v_and_b32_e32 v25, 0xffff0000, v19
	v_mul_f32_e32 v19, 0xbfb8aa3b, v27
	v_exp_f32_e32 v18, v18
	v_exp_f32_e32 v19, v19
	s_waitcnt lgkmcnt(2)
	v_pk_fma_f32 v[20:21], v[30:31], v[36:37], v[56:57] op_sel_hi:[1,0,1]
	v_pk_add_f32 v[18:19], v[18:19], 1.0 op_sel_hi:[1,0]
	v_pk_fma_f32 v[20:21], v[32:33], v[24:25], v[20:21] op_sel_hi:[0,1,1]
	s_nop 0
	v_rcp_f32_e32 v19, v19
	s_nop 0
	v_mul_f32_e32 v19, v27, v19
	s_nop 0
	v_rcp_f32_e32 v18, v18
	s_nop 0
	v_mul_f32_e32 v18, v26, v18
	v_pk_mul_f32 v[18:19], v[20:21], v[18:19]
	v_cvt_pk_bf16_f32 v20, v22, v23
	v_cvt_pk_bf16_f32 v21, v18, v19
	global_store_dwordx2 v[16:17], v[20:21], off offset:48
	global_load_dwordx2 v[18:19], v[42:43], off offset:64
	s_nop 0
	global_load_dwordx2 v[20:21], v[40:41], off offset:1344
	s_waitcnt vmcnt(1)
	v_lshlrev_b32_e32 v24, 16, v18
	s_waitcnt vmcnt(0)
	v_lshlrev_b32_e32 v26, 16, v20
	v_and_b32_e32 v20, 0xffff0000, v20
	v_mul_f32_e32 v22, 0xbfb8aa3b, v26
	v_and_b32_e32 v25, 0xffff0000, v18
	v_mul_f32_e32 v18, 0xbfb8aa3b, v20
	v_exp_f32_e32 v22, v22
	v_exp_f32_e32 v23, v18
	v_pk_fma_f32 v[0:1], v[32:33], v[24:25], v[0:1] op_sel_hi:[0,1,1]
	v_pk_add_f32 v[22:23], v[22:23], 1.0 op_sel_hi:[1,0]
	s_nop 0
	s_nop 0
	v_rcp_f32_e32 v23, v23
	s_nop 0
	v_mul_f32_e32 v23, v20, v23
	s_nop 0
	v_rcp_f32_e32 v22, v22
	s_nop 0
	v_mul_f32_e32 v22, v26, v22
	v_pk_mul_f32 v[0:1], v[0:1], v[22:23]
	v_lshlrev_b32_e32 v22, 16, v21
	v_and_b32_e32 v23, 0xffff0000, v21
	v_mul_f32_e32 v18, 0xbfb8aa3b, v22
	v_lshlrev_b32_e32 v20, 16, v19
	v_and_b32_e32 v21, 0xffff0000, v19
	v_mul_f32_e32 v19, 0xbfb8aa3b, v23
	v_exp_f32_e32 v18, v18
	v_exp_f32_e32 v19, v19
	v_pk_fma_f32 v[2:3], v[32:33], v[20:21], v[2:3] op_sel_hi:[0,1,1]
	v_cvt_pk_bf16_f32 v0, v0, v1
	v_pk_add_f32 v[18:19], v[18:19], 1.0 op_sel_hi:[1,0]
	s_nop 0
	s_nop 0
	v_rcp_f32_e32 v19, v19
	s_nop 0
	v_mul_f32_e32 v19, v23, v19
	s_nop 0
	v_rcp_f32_e32 v18, v18
	s_nop 0
	v_mul_f32_e32 v18, v22, v18
	v_pk_mul_f32 v[2:3], v[2:3], v[18:19]
	s_nop 0
	v_cvt_pk_bf16_f32 v1, v2, v3
	global_store_dwordx2 v[16:17], v[0:1], off offset:64
	global_load_dwordx2 v[0:1], v[42:43], off offset:80
	s_nop 0
	global_load_dwordx2 v[2:3], v[40:41], off offset:1360
	s_waitcnt vmcnt(1)
; DI float lo16(unsigned w) { return __uint_as_float(w << 16); }
; DI float hi16(unsigned w) { return __uint_as_float(w & 0xffff0000u); }
; DI float siluf_(float x) { return x / (1.f + __expf(-x)); }
; DI void nsa_item(const Params& p, int it, char* lds) {
;     ...
; #pragma unroll
;   for (int db = 0; db < 2; ++db)
; #pragma unroll
;     for (int g = 0; g < 4; ++g) {
;       const int col = h * 64 + 32 * db + 8 * g + 4 * hi;
;       const u32x2 w = *(const u32x2*)(ow + tok * 256 + col), az = *(const u32x2*)(proj + tok * NP + C_AZ + col);
;       const float v0 = (ya[db][4 * g] + o[db][4 * g] * il + g2 * lo16(w[0])) * siluf_(lo16(az[0]));
;       const float v1 = (ya[db][4 * g + 1] + o[db][4 * g + 1] * il + g2 * hi16(w[0])) * siluf_(hi16(az[0]));
;       const float v2 = (ya[db][4 * g + 2] + o[db][4 * g + 2] * il + g2 * lo16(w[1])) * siluf_(lo16(az[1]));
;       const float v3 = (ya[db][4 * g + 3] + o[db][4 * g + 3] * il + g2 * hi16(w[1])) * siluf_(hi16(az[1]));
;       u32x2 v; v[0] = pk2(v0, v1); v[1] = pk2(v2, v3);
;       *(u32x2*)(y + tok * 1024 + col) = v;
;     }
; __global__ void __launch_bounds__(256, 2) hybrid_megakernel(Params p) {
;     ...
;       const int gi = vb >> 4;
;       int start = 0, mine = 0;
;       for (int g2 = 0; g2 <= gi; ++g2) {
;         const int n = 32 - g2;
;         const int d = (n <= 10) ? 2 : (n <= 22) ? 1 : 0;
;         if (g2 < gi) start += 2 * d; else mine = d;
;       }
;       start += ((vb >> 3) & 1) * mine;
;       const int x = vb & 7;
;       for (int k = 0; k < mine; ++k) { const int slot = start + k; sgu_item(p, l, slot * 8 + x, lds); pool_item(p, l, slot * 8 + x, lds); dilcomb_item(p, x * 64 + slot); }
	v_lshlrev_b32_e32 v20, 16, v0
	s_waitcnt vmcnt(0)
	v_lshlrev_b32_e32 v22, 16, v2
	v_and_b32_e32 v2, 0xffff0000, v2
	v_mul_f32_e32 v18, 0xbfb8aa3b, v22
	v_and_b32_e32 v21, 0xffff0000, v0
	v_mul_f32_e32 v0, 0xbfb8aa3b, v2
	v_exp_f32_e32 v18, v18
	v_exp_f32_e32 v19, v0
	v_pk_fma_f32 v[4:5], v[32:33], v[20:21], v[4:5] op_sel_hi:[0,1,1]
	v_pk_add_f32 v[18:19], v[18:19], 1.0 op_sel_hi:[1,0]
	s_nop 0
	s_nop 0
	v_rcp_f32_e32 v19, v19
	s_nop 0
	v_mul_f32_e32 v19, v2, v19
	s_nop 0
	v_rcp_f32_e32 v18, v18
	s_nop 0
	v_mul_f32_e32 v18, v22, v18
	v_pk_mul_f32 v[4:5], v[4:5], v[18:19]
	v_lshlrev_b32_e32 v18, 16, v3
	v_and_b32_e32 v19, 0xffff0000, v3
	v_mul_f32_e32 v0, 0xbfb8aa3b, v18
	v_pk_fma_f32 v[2:3], v[6:7], v[36:37], v[48:49] op_sel_hi:[1,0,1]
	v_lshlrev_b32_e32 v6, 16, v1
	v_and_b32_e32 v7, 0xffff0000, v1
	v_mul_f32_e32 v1, 0xbfb8aa3b, v19
	v_exp_f32_e32 v0, v0
	v_exp_f32_e32 v1, v1
	v_pk_fma_f32 v[2:3], v[32:33], v[6:7], v[2:3] op_sel_hi:[0,1,1]
	v_pk_add_f32 v[0:1], v[0:1], 1.0 op_sel_hi:[1,0]
	s_nop 0
	s_nop 0
	v_rcp_f32_e32 v1, v1
	s_nop 0
	v_mul_f32_e32 v1, v19, v1
	s_nop 0
	v_rcp_f32_e32 v0, v0
	s_nop 0
	v_mul_f32_e32 v0, v18, v0
	v_pk_mul_f32 v[0:1], v[2:3], v[0:1]
	v_cvt_pk_bf16_f32 v2, v4, v5
	v_cvt_pk_bf16_f32 v3, v0, v1
	global_store_dwordx2 v[16:17], v[2:3], off offset:80
	global_load_dwordx2 v[0:1], v[42:43], off offset:96
	s_nop 0
	global_load_dwordx2 v[2:3], v[40:41], off offset:1376
	v_pk_fma_f32 v[6:7], v[8:9], v[36:37], v[46:47] op_sel_hi:[1,0,1]
	s_waitcnt vmcnt(1)
	v_lshlrev_b32_e32 v8, 16, v0
	s_waitcnt vmcnt(0)
	v_lshlrev_b32_e32 v18, 16, v2
	v_and_b32_e32 v2, 0xffff0000, v2
	v_mul_f32_e32 v4, 0xbfb8aa3b, v18
	v_and_b32_e32 v9, 0xffff0000, v0
	v_mul_f32_e32 v0, 0xbfb8aa3b, v2
	v_exp_f32_e32 v4, v4
	v_exp_f32_e32 v5, v0
	v_pk_fma_f32 v[6:7], v[32:33], v[8:9], v[6:7] op_sel_hi:[0,1,1]
	v_pk_add_f32 v[4:5], v[4:5], 1.0 op_sel_hi:[1,0]
	s_nop 0
	s_nop 0
	v_rcp_f32_e32 v5, v5
	s_nop 0
	v_mul_f32_e32 v5, v2, v5
	s_nop 0
	v_rcp_f32_e32 v4, v4
	s_nop 0
	v_mul_f32_e32 v4, v18, v4
	v_lshlrev_b32_e32 v8, 16, v3
	v_and_b32_e32 v9, 0xffff0000, v3
	v_pk_mul_f32 v[4:5], v[6:7], v[4:5]
	v_mul_f32_e32 v0, 0xbfb8aa3b, v8
	v_lshlrev_b32_e32 v6, 16, v1
	v_and_b32_e32 v7, 0xffff0000, v1
	v_mul_f32_e32 v1, 0xbfb8aa3b, v9
	v_exp_f32_e32 v0, v0
	v_exp_f32_e32 v1, v1
	v_pk_fma_f32 v[2:3], v[10:11], v[36:37], v[44:45] op_sel_hi:[1,0,1]
	v_pk_add_f32 v[0:1], v[0:1], 1.0 op_sel_hi:[1,0]
	v_pk_fma_f32 v[2:3], v[32:33], v[6:7], v[2:3] op_sel_hi:[0,1,1]
	s_nop 0
	v_rcp_f32_e32 v1, v1
	s_nop 0
	v_mul_f32_e32 v1, v9, v1
	s_nop 0
	v_rcp_f32_e32 v0, v0
	s_nop 0
	v_mul_f32_e32 v0, v8, v0
	v_pk_mul_f32 v[0:1], v[2:3], v[0:1]
	v_cvt_pk_bf16_f32 v2, v4, v5
	v_cvt_pk_bf16_f32 v3, v0, v1
	global_store_dwordx2 v[16:17], v[2:3], off offset:96
	global_load_dwordx2 v[0:1], v[42:43], off offset:112
	s_nop 0
	global_load_dwordx2 v[2:3], v[40:41], off offset:1392
	v_pk_fma_f32 v[6:7], v[12:13], v[36:37], v[38:39] op_sel_hi:[1,0,1]
	s_waitcnt vmcnt(1)
	v_lshlrev_b32_e32 v8, 16, v0
	s_waitcnt vmcnt(0)
	v_lshlrev_b32_e32 v10, 16, v2
	v_and_b32_e32 v2, 0xffff0000, v2
	v_mul_f32_e32 v4, 0xbfb8aa3b, v10
	v_and_b32_e32 v9, 0xffff0000, v0
	v_mul_f32_e32 v0, 0xbfb8aa3b, v2
	v_exp_f32_e32 v4, v4
	v_exp_f32_e32 v5, v0
	v_pk_fma_f32 v[6:7], v[32:33], v[8:9], v[6:7] op_sel_hi:[0,1,1]
	v_pk_add_f32 v[4:5], v[4:5], 1.0 op_sel_hi:[1,0]
	s_nop 0
	s_nop 0
	v_rcp_f32_e32 v5, v5
	s_nop 0
	v_mul_f32_e32 v5, v2, v5
	s_nop 0
	v_rcp_f32_e32 v4, v4
	s_nop 0
	v_mul_f32_e32 v4, v10, v4
	v_lshlrev_b32_e32 v8, 16, v3
	v_and_b32_e32 v9, 0xffff0000, v3
	v_pk_mul_f32 v[4:5], v[6:7], v[4:5]
	v_mul_f32_e32 v0, 0xbfb8aa3b, v8
	v_lshlrev_b32_e32 v6, 16, v1
	v_and_b32_e32 v7, 0xffff0000, v1
	v_mul_f32_e32 v1, 0xbfb8aa3b, v9
	v_exp_f32_e32 v0, v0
	v_exp_f32_e32 v1, v1
	s_waitcnt lgkmcnt(0)
	v_pk_fma_f32 v[2:3], v[14:15], v[36:37], v[34:35] op_sel_hi:[1,0,1]
	v_pk_add_f32 v[0:1], v[0:1], 1.0 op_sel_hi:[1,0]
	v_pk_fma_f32 v[2:3], v[32:33], v[6:7], v[2:3] op_sel_hi:[0,1,1]
	s_nop 0
	v_rcp_f32_e32 v1, v1
	s_nop 0
	v_mul_f32_e32 v1, v9, v1
	s_ashr_i32 s0, s13, 4
	s_cmp_lt_i32 s0, 0
	v_rcp_f32_e32 v0, v0
	s_nop 0
	v_mul_f32_e32 v0, v8, v0
	v_pk_mul_f32 v[0:1], v[2:3], v[0:1]
	v_cvt_pk_bf16_f32 v2, v4, v5
	v_cvt_pk_bf16_f32 v3, v0, v1
	global_store_dwordx2 v[16:17], v[2:3], off offset:112
	s_cmp_ge_u32 s0, 2
	s_cselect_b32 s1, 1, 0
	s_cmp_ge_u32 s0, 30
	s_cselect_b32 s2, 1, 0
	s_add_u32 s1, s1, s2
	s_sub_i32 s2, s0, 2
	s_max_i32 s2, s2, 0
	s_sub_i32 s4, s0, 30
	s_max_i32 s4, s4, 0
	s_add_i32 s2, s2, s4
	s_lshl_b32 s2, s2, 1
	v_mov_b32_e32 v116, s1
	v_mov_b32_e32 v0, s2
	s_cmp_eq_u32 s1, 0
	s_cbranch_scc1 .LBB0_345
